# one static priority raise (s_setprio 1) for the younger wave half (waves 4-7) during the eight GEMM phases
# baseline (speedup 1.0000x reference)
.LBB0_139:
	s_add_u32 s50, s80, 0xa200000
	s_addc_u32 s51, s81, 0
	s_add_u32 s96, s80, 0xe200000
	s_addc_u32 s88, s81, 0
	s_cmp_lt_i32 s62, 2
	s_cselect_b64 s[0:1], -1, 0
	s_cmp_gt_i32 s63, 1
	s_cselect_b64 s[2:3], -1, 0
	v_writelane_b32 v255, s46, 25
	s_and_b64 s[0:1], s[0:1], s[2:3]
	s_andn2_b64 vcc, exec, s[0:1]
	v_writelane_b32 v255, s47, 26
	s_mov_b32 s97, s93
	s_cbranch_vccnz .LBB0_263
	v_readfirstlane_b32 s0, v212
	s_cmp_lt_u32 s0, 0x100
	s_cbranch_scc1 .Lmy_gpr_1
	s_setprio 1
.Lmy_gpr_1:
	v_mov_b32_e32 v0, v212
	s_waitcnt vmcnt(0)
	s_cmpk_lt_i32 s93, 0x800
	s_cselect_b64 s[0:1], -1, 0
	s_cmpk_gt_i32 s93, 0x7ff
	v_readfirstlane_b32 s10, v212
	s_cbranch_scc1 .LBB0_146
	s_ashr_i32 s2, s93, 31
	s_lshr_b32 s2, s2, 29
	s_add_i32 s4, s93, s2
	s_and_b32 s2, s4, -8
	s_sub_i32 s5, s93, s2
	s_cmp_gt_i32 s5, -1
	s_cbranch_scc0 .LBB0_143
	s_lshl_b32 s6, s5, 8
	s_cbranch_execz .LBB0_144
	s_branch .LBB0_145

.LBB0_263:
	s_setprio 0
	s_and_b32 s0, s85, 0x3fffffc0
	s_lshl_b32 s0, s0, 2
	s_add_i32 s0, s0, 0
	s_add_i32 s0, s0, 0x20000
	s_cmp_lt_i32 s62, 3
	v_writelane_b32 v255, s0, 27
	s_cselect_b64 s[0:1], -1, 0
	s_cmp_gt_i32 s63, 2
	s_cselect_b64 s[2:3], -1, 0
	s_and_b64 s[0:1], s[0:1], s[2:3]
	s_andn2_b64 vcc, exec, s[0:1]
	s_cbranch_vccnz .LBB0_356
	v_mov_b32_e32 v0, v212
	v_readlane_b32 s0, v255, 7
	v_and_b32_e32 v0, 63, v0
	v_lshlrev_b32_e32 v0, 2, v0
	v_readlane_b32 s12, v255, 19
	v_readlane_b32 s13, v255, 20
	s_nop 4
	global_load_dword v1, v0, s[12:13] offset:768
	global_load_dword v2, v0, s[12:13] offset:1024
	global_load_dword v3, v0, s[12:13] offset:1792
	global_load_dword v4, v0, s[12:13] offset:1280
	global_load_dword v5, v0, s[12:13] offset:256
	global_load_dword v6, v0, s[12:13] offset:512
	global_load_dword v7, v0, s[12:13]
	s_nop 0
	global_load_dword v0, v0, s[12:13] offset:1536
	v_mbcnt_lo_u32_b32 v8, -1, 0
	v_mbcnt_hi_u32_b32 v8, -1, v8
	v_and_b32_e32 v9, 64, v8
	v_xor_b32_e32 v10, 1, v8
	v_add_u32_e32 v9, 64, v9
	v_cmp_lt_i32_e32 vcc, v10, v9
	v_xor_b32_e32 v11, 2, v8
	v_xor_b32_e32 v12, 4, v8
	v_cndmask_b32_e32 v10, v8, v10, vcc
	v_lshlrev_b32_e32 v213, 2, v10
	v_cmp_lt_i32_e32 vcc, v11, v9
	v_xor_b32_e32 v13, 8, v8
	v_xor_b32_e32 v14, 16, v8
	v_xor_b32_e32 v15, 32, v8
	v_readlane_b32 s5, v255, 12
	s_cmpk_gt_i32 s84, 0x3ff
	s_mov_b32 s5, 0
	v_readlane_b32 s1, v255, 8
	v_readlane_b32 s2, v255, 9
	v_readlane_b32 s3, v255, 10
	v_readlane_b32 s4, v255, 11
	v_readlane_b32 s6, v255, 13
	v_readlane_b32 s7, v255, 14
	v_readlane_b32 s8, v255, 15
	v_readlane_b32 s9, v255, 16
	v_readlane_b32 s10, v255, 17
	v_readlane_b32 s11, v255, 18
	v_readlane_b32 s14, v255, 21
	v_readlane_b32 s15, v255, 22
	s_waitcnt vmcnt(0)
	v_mul_f32_e32 v3, v4, v3
	v_mul_f32_e32 v1, v5, v1
	v_cndmask_b32_e32 v4, v8, v11, vcc
	v_fmac_f32_e32 v1, v7, v6
	v_fmac_f32_e32 v3, v2, v0
	ds_bpermute_b32 v0, v213, v1
	ds_bpermute_b32 v2, v213, v3
	v_lshlrev_b32_e32 v214, 2, v4
	v_cmp_lt_i32_e32 vcc, v12, v9
	s_waitcnt lgkmcnt(0)
	v_add_f32_e32 v0, v1, v0
	v_add_f32_e32 v1, v3, v2
	ds_bpermute_b32 v2, v214, v0
	ds_bpermute_b32 v3, v214, v1
	v_cndmask_b32_e32 v4, v8, v12, vcc
	v_lshlrev_b32_e32 v215, 2, v4
	v_cmp_lt_i32_e32 vcc, v13, v9
	s_waitcnt lgkmcnt(1)
	v_add_f32_e32 v0, v0, v2
	s_waitcnt lgkmcnt(0)
	v_add_f32_e32 v1, v1, v3
	ds_bpermute_b32 v2, v215, v0
	ds_bpermute_b32 v3, v215, v1
	v_cndmask_b32_e32 v4, v8, v13, vcc
	v_lshlrev_b32_e32 v216, 2, v4
	v_cmp_lt_i32_e32 vcc, v14, v9
	s_waitcnt lgkmcnt(1)
	v_add_f32_e32 v0, v0, v2
	s_waitcnt lgkmcnt(0)
	v_add_f32_e32 v1, v1, v3
	ds_bpermute_b32 v2, v216, v0
	ds_bpermute_b32 v3, v216, v1
	v_cndmask_b32_e32 v4, v8, v14, vcc
	v_lshlrev_b32_e32 v217, 2, v4
	v_cmp_lt_i32_e32 vcc, v15, v9
	s_waitcnt lgkmcnt(1)
	v_add_f32_e32 v0, v0, v2
	s_waitcnt lgkmcnt(0)
	v_add_f32_e32 v1, v1, v3
	ds_bpermute_b32 v2, v217, v0
	ds_bpermute_b32 v3, v217, v1
	v_cndmask_b32_e32 v4, v8, v15, vcc
	v_lshlrev_b32_e32 v218, 2, v4
	s_waitcnt lgkmcnt(1)
	v_add_f32_e32 v2, v0, v2
	s_waitcnt lgkmcnt(0)
	v_add_f32_e32 v0, v1, v3
	ds_bpermute_b32 v3, v218, v2
	ds_bpermute_b32 v1, v218, v0
	s_cbranch_scc1 .LBB0_302
	s_waitcnt lgkmcnt(1)
	v_add_f32_e32 v2, v2, v3
	s_mov_b32 s0, 0x3fb8aa3b
	v_mul_f32_e32 v3, 0x3fb8aa3b, v2
	v_fma_f32 v4, v2, s0, -v3
	v_rndne_f32_e32 v5, v3
	v_fmac_f32_e32 v4, 0x32a5705f, v2
	v_sub_f32_e32 v3, v3, v5
	v_add_f32_e32 v3, v3, v4
	v_exp_f32_e32 v3, v3
	v_cvt_i32_f32_e32 v4, v5
	s_waitcnt lgkmcnt(0)
	v_add_f32_e32 v0, v0, v1
	s_mov_b32 s1, 0xc2ce8ed0
	v_cmp_ngt_f32_e32 vcc, s1, v2
	v_ldexp_f32 v1, v3, v4
	v_mul_f32_e32 v3, 0x3fb8aa3b, v0
	v_fma_f32 v4, v0, s0, -v3
	v_rndne_f32_e32 v5, v3
	v_fmac_f32_e32 v4, 0x32a5705f, v0
	v_sub_f32_e32 v3, v3, v5
	v_add_f32_e32 v3, v3, v4
	v_exp_f32_e32 v3, v3
	v_cvt_i32_f32_e32 v4, v5
	s_mov_b32 s2, 0x42b17218
	v_cndmask_b32_e32 v1, 0, v1, vcc
	v_mov_b32_e32 v5, 0x7f800000
	v_cmp_nlt_f32_e32 vcc, s2, v2
	v_ldexp_f32 v2, v3, v4
	v_bfe_u32 v222, v212, 5, 1
	v_cndmask_b32_e32 v1, v5, v1, vcc
	v_cmp_ngt_f32_e32 vcc, s1, v0
	v_bfe_u32 v3, v212, 2, 2
	v_lshlrev_b32_e32 v223, 2, v222
	v_cndmask_b32_e32 v2, 0, v2, vcc
	v_cmp_nlt_f32_e32 vcc, s2, v0
	v_lshrrev_b32_e32 v6, 3, v212
	v_and_b32_e32 v221, 31, v212
	v_cndmask_b32_e32 v0, v5, v2, vcc
	v_or_b32_e32 v5, v223, v3
	v_lshlrev_b32_e32 v3, 2, v3
	v_and_b32_e32 v6, 2, v6
	v_bfe_u32 v7, v212, 1, 1
	v_sub_f32_e32 v0, v1, v0
	s_add_u32 s17, s80, 0x12200000
	v_or3_b32 v3, v3, v6, v7
	v_lshlrev_b32_e32 v6, 3, v212
	v_lshlrev_b32_e32 v5, 9, v5
	v_lshlrev_b32_e32 v194, 2, v221
	v_readlane_b32 s0, v255, 27
	v_add_f32_e32 v219, 0x3e4ccccd, v0
	s_addc_u32 s20, s81, 0
	v_lshlrev_b32_e32 v0, 3, v221
	v_mov_b32_e32 v1, 0
	v_and_b32_e32 v6, 8, v6
	v_lshl_or_b32 v3, v3, 4, v5
	v_add_u32_e32 v226, s0, v194
	v_lshl_add_u32 v227, v222, 4, s0
	s_movk_i32 s0, 0x80
	v_readlane_b32 s52, v255, 7
	s_add_u32 s21, s80, 0x16200000
	v_bitop3_b32 v0, v0, v212, 32 bitop3:0x78
	v_lshlrev_b32_e32 v2, 7, v221
	v_lshlrev_b32_e32 v4, 3, v222
	v_lshlrev_b32_e32 v5, 9, v222
	v_lshlrev_b32_e32 v7, 4, v221
	v_bitop3_b32 v229, v3, s0, v6 bitop3:0x36
	s_movk_i32 s0, 0xc0
	v_mov_b32_e32 v195, v1
	v_readlane_b32 s66, v255, 21
	v_readlane_b32 s67, v255, 22
	s_addc_u32 s22, s81, 0
	v_and_b32_e32 v220, 63, v212
	v_or_b32_e32 v224, v3, v6
	v_add3_u32 v225, 0, v5, v7
	v_bitop3_b32 v228, v3, 64, v6 bitop3:0x36
	v_bitop3_b32 v230, v3, s0, v6 bitop3:0x36
	v_lshl_add_u64 v[196:197], s[66:67], 0, v[194:195]
	v_or_b32_e32 v231, 9, v223
	v_or_b32_e32 v232, 10, v223
	v_or_b32_e32 v233, 11, v223
	v_or_b32_e32 v234, 16, v223
	v_or_b32_e32 v235, 17, v223
	v_or_b32_e32 v236, 18, v223
	v_or_b32_e32 v237, 19, v223
	v_or_b32_e32 v238, 24, v223
	v_or_b32_e32 v239, 25, v223
	v_or_b32_e32 v240, 26, v223
	v_or_b32_e32 v241, 27, v223
	v_or_b32_e32 v242, 0x42, v222
	v_or_b32_e32 v243, 64, v222
	s_mov_b64 s[6:7], 0x200000
	v_lshlrev_b32_e32 v198, 1, v0
	s_mov_b64 s[8:9], 0x2000
	s_mov_b64 s[10:11], 0x202000
	v_lshlrev_b32_e32 v200, 1, v2
	v_lshlrev_b32_e32 v202, 1, v4
	s_mov_b64 s[12:13], 0x4000
	s_mov_b64 s[14:15], 0x204000
	s_add_i32 s23, 0, 0x10000
	s_mov_b32 s24, 0xf149f2ca
	s_mov_b64 s[18:19], 0x6000
	v_mov_b32_e32 v244, 0x358637bd
	s_mov_b32 s25, 0xf800000
	v_mov_b32_e32 v245, 0x260
	s_mov_b32 s26, 0x3f4ccccd
	s_mov_b32 s27, 0xa200000
	s_mov_b32 s28, 0x1a202000
	s_mov_b32 s29, 0xa202000
	s_mov_b32 s30, 0x1a204000
	s_mov_b32 s31, 0xa204000
	s_mov_b32 s34, 0x1a206000
	s_mov_b32 s35, 0xa206000
	v_mov_b32_e32 v246, 0xf149f2ca
	s_mov_b32 s36, s84
	v_readlane_b32 s53, v255, 8
	v_readlane_b32 s54, v255, 9
	v_readlane_b32 s55, v255, 10
	v_readlane_b32 s56, v255, 11
	v_readlane_b32 s57, v255, 12
	v_readlane_b32 s58, v255, 13
	v_readlane_b32 s59, v255, 14
	v_readlane_b32 s60, v255, 15
	v_readlane_b32 s61, v255, 16
	v_readlane_b32 s62, v255, 17
	v_readlane_b32 s63, v255, 18
	v_readlane_b32 s64, v255, 19
	v_readlane_b32 s65, v255, 20
	s_branch .LBB0_267

.LBB0_356:
	s_cmp_lt_i32 s62, 4
	s_cselect_b64 s[0:1], -1, 0
	s_cmp_gt_i32 s63, 3
	s_cselect_b64 s[2:3], -1, 0
	s_and_b64 s[0:1], s[0:1], s[2:3]
	s_andn2_b64 vcc, exec, s[0:1]
	s_cbranch_vccnz .LBB0_435
	v_readfirstlane_b32 s0, v212
	s_cmp_lt_u32 s0, 0x100
	s_cbranch_scc1 .Lmy_gpr_3
	s_setprio 1
.Lmy_gpr_3:
	v_mov_b32_e32 v0, v212
	s_waitcnt vmcnt(0)
	s_cmpk_gt_i32 s93, 0x1ff
	v_readfirstlane_b32 s3, v212
	s_cbranch_scc1 .LBB0_381
	s_ashr_i32 s17, s93, 31
	s_lshr_b32 s0, s17, 29
	s_add_i32 s4, s93, s0
	s_and_b32 s0, s4, -8
	s_sub_i32 s5, s93, s0
	s_cmp_gt_i32 s5, -1
	s_cbranch_scc0 .LBB0_360
	s_lshl_b32 s2, s5, 6
	s_cbranch_execz .LBB0_361
	s_branch .LBB0_362

.LBB0_435:
	s_setprio 0
	s_cmp_lt_i32 s62, 5
	s_cselect_b64 s[0:1], -1, 0
	s_cmp_gt_i32 s63, 4
	s_cselect_b64 s[2:3], -1, 0
	s_and_b64 s[0:1], s[0:1], s[2:3]
	s_andn2_b64 vcc, exec, s[0:1]
	s_cbranch_vccnz .LBB0_493
	v_readlane_b32 s0, v255, 25
	v_mov_b32_e32 v0, v212
	s_cmpk_gt_i32 s0, 0x3fff
	v_readlane_b32 s10, v255, 23
	v_readlane_b32 s1, v255, 26
	v_readlane_b32 s11, v255, 24
	s_cbranch_scc1 .LBB0_439
	v_and_b32_e32 v4, 63, v0
	v_mbcnt_lo_u32_b32 v0, -1, 0
	v_mbcnt_hi_u32_b32 v0, -1, v0
	s_waitcnt lgkmcnt(0)
	v_and_b32_e32 v1, 64, v0
	v_add_u32_e32 v1, 64, v1
	v_xor_b32_e32 v2, 1, v0
	v_cmp_lt_i32_e32 vcc, v2, v1
	v_readlane_b32 s52, v255, 7
	v_readlane_b32 s56, v255, 11
	v_cndmask_b32_e32 v2, v0, v2, vcc
	v_lshlrev_b32_e32 v26, 2, v2
	v_xor_b32_e32 v2, 2, v0
	v_cmp_lt_i32_e32 vcc, v2, v1
	v_readlane_b32 s57, v255, 12
	s_mov_b64 s[0:1], 0x2000
	v_cndmask_b32_e32 v2, v0, v2, vcc
	v_lshlrev_b32_e32 v27, 2, v2
	v_xor_b32_e32 v2, 4, v0
	v_cmp_lt_i32_e32 vcc, v2, v1
	v_readlane_b32 s53, v255, 8
	v_readlane_b32 s54, v255, 9
	v_cndmask_b32_e32 v2, v0, v2, vcc
	v_lshlrev_b32_e32 v28, 2, v2
	v_xor_b32_e32 v2, 8, v0
	v_cmp_lt_i32_e32 vcc, v2, v1
	v_readlane_b32 s55, v255, 10
	v_readlane_b32 s58, v255, 13
	v_cndmask_b32_e32 v2, v0, v2, vcc
	v_lshlrev_b32_e32 v29, 2, v2
	v_xor_b32_e32 v2, 16, v0
	v_cmp_lt_i32_e32 vcc, v2, v1
	v_readlane_b32 s59, v255, 14
	v_readlane_b32 s60, v255, 15
	v_cndmask_b32_e32 v2, v0, v2, vcc
	v_lshlrev_b32_e32 v30, 2, v2
	v_xor_b32_e32 v2, 32, v0
	v_cmp_lt_i32_e32 vcc, v2, v1
	v_mov_b32_e32 v1, 0
	v_readlane_b32 s61, v255, 16
	v_cndmask_b32_e32 v0, v0, v2, vcc
	v_lshlrev_b32_e32 v31, 2, v0
	v_lshlrev_b32_e32 v0, 4, v4
	v_lshl_add_u64 v[2:3], s[56:57], 0, v[0:1]
	v_lshl_add_u64 v[12:13], v[2:3], 0, s[0:1]
	s_mov_b64 s[0:1], 0x3000
	v_lshl_add_u64 v[14:15], v[2:3], 0, s[0:1]
	s_mov_b64 s[0:1], 0x3400
	v_lshl_add_u64 v[16:17], v[2:3], 0, s[0:1]
	s_mov_b64 s[0:1], 0x3800
	v_lshl_add_u64 v[18:19], v[2:3], 0, s[0:1]
	s_mov_b64 s[0:1], 0x3c00
	v_lshl_add_u64 v[20:21], v[2:3], 0, s[0:1]
	v_readlane_b32 s0, v255, 25
	v_readlane_b32 s1, v255, 26
	s_mov_b32 s8, s0
	s_ashr_i32 s9, s0, 31
	s_lshl_b64 s[0:1], s[8:9], 13
	s_add_u32 s0, s78, s0
	s_addc_u32 s1, s79, s1
	v_lshl_add_u64 v[2:3], s[0:1], 0, v[0:1]
	s_mov_b64 s[0:1], 0x1000
	s_ashr_i32 s11, s10, 31
	v_lshl_add_u64 v[22:23], v[2:3], 0, s[0:1]
	s_lshl_b64 s[2:3], s[10:11], 13
	s_lshl_b64 s[0:1], s[8:9], 12
	s_add_u32 s0, s80, s0
	v_lshlrev_b32_e32 v0, 3, v4
	s_addc_u32 s1, s81, s1
	v_lshl_add_u64 v[0:1], s[0:1], 0, v[0:1]
	s_mov_b64 s[0:1], 0xa200000
	v_lshl_add_u64 v[24:25], v[0:1], 0, s[0:1]
	s_mov_b32 s0, s8
	v_readlane_b32 s62, v255, 17
	v_readlane_b32 s63, v255, 18
	v_readlane_b32 s64, v255, 19
	v_readlane_b32 s65, v255, 20
	v_readlane_b32 s66, v255, 21
	v_readlane_b32 s67, v255, 22
	v_writelane_b32 v255, s0, 25
	s_lshl_b64 s[4:5], s[10:11], 12
	v_mov_b32_e32 v32, 0x358637bd
	s_mov_b32 s6, 0xf800000
	v_mov_b32_e32 v33, 0x260
	v_writelane_b32 v255, s1, 26
	s_mov_b32 s7, s8
	global_load_dwordx4 v[132:135], v[12:13], off offset:1024
	global_load_dwordx4 v[136:139], v[12:13], off offset:2048
	global_load_dwordx4 v[140:143], v[12:13], off offset:3072
	global_load_dwordx4 v[144:147], v[14:15], off
	global_load_dwordx4 v[148:151], v[16:17], off
	global_load_dwordx4 v[152:155], v[18:19], off
	global_load_dwordx4 v[156:159], v[20:21], off

.LBB0_493:
	s_cmp_lt_i32 s62, 6
	s_cselect_b64 s[0:1], -1, 0
	s_cmp_gt_i32 s63, 5
	s_cselect_b64 s[2:3], -1, 0
	s_and_b64 s[0:1], s[0:1], s[2:3]
	s_andn2_b64 vcc, exec, s[0:1]
	s_cbranch_vccnz .LBB0_648
	v_readfirstlane_b32 s0, v212
	s_cmp_lt_u32 s0, 0x100
	s_cbranch_scc1 .Lmy_gpr_5
	s_setprio 1
.Lmy_gpr_5:
	v_mov_b32_e32 v147, v212
	s_waitcnt vmcnt(0)
	s_cmpk_lt_i32 s93, 0x480
	s_cselect_b64 s[0:1], -1, 0
	s_cmpk_gt_i32 s93, 0x47f
	v_readfirstlane_b32 s2, v212
	s_cbranch_scc1 .LBB0_496
	s_ashr_i32 s3, s93, 31
	s_lshr_b32 s3, s3, 29
	s_add_i32 s3, s93, s3
	s_ashr_i32 s4, s3, 3
	s_and_b32 s3, s3, -8
	s_sub_i32 s3, s93, s3
	s_cmp_lt_i32 s3, 0
	s_movk_i32 s5, 0x91
	s_cselect_b32 s5, s5, 0x90
	s_mul_i32 s3, s3, s5
	s_add_i32 s3, s3, s4
	s_mul_hi_i32 s4, s3, 0x38e38e39
	s_lshr_b32 s5, s4, 31
	s_ashr_i32 s4, s4, 5
	s_add_i32 s4, s4, s5
	s_lshl_b32 s5, s4, 3
	s_mulk_i32 s4, 0x90
	s_sub_i32 s3, s3, s4
	s_sext_i32_i16 s4, s3
	s_bfe_u32 s4, s4, 0x3001c
	s_add_i32 s4, s3, s4
	s_sext_i32_i16 s6, s4
	s_and_b32 s4, s4, 0xfff8
	s_sub_i32 s3, s3, s4
	s_sext_i32_i16 s3, s3
	s_add_i32 s28, s5, s3
	s_ashr_i32 s26, s6, 3

.LBB0_648:
	s_setprio 0
	s_cmp_lt_i32 s62, 7
	s_cselect_b64 s[0:1], -1, 0
	s_cmp_gt_i32 s63, 6
	s_cselect_b64 s[2:3], -1, 0
	s_and_b64 s[0:1], s[0:1], s[2:3]
	s_andn2_b64 vcc, exec, s[0:1]
	s_cbranch_vccnz .LBB0_718
	v_mov_b32_e32 v0, v212
	s_cmpk_gt_i32 s84, 0x1ff
	s_cbranch_scc1 .LBB0_664
	s_waitcnt lgkmcnt(0)
	v_and_b32_e32 v3, 7, v212
	v_lshlrev_b32_e32 v80, 4, v3
	v_mov_b32_e32 v81, 0
	v_lshl_add_u64 v[0:1], s[80:81], 0, v[80:81]
	s_mov_b64 s[0:1], 0x12a00000
	v_lshl_add_u64 v[82:83], v[0:1], 0, s[0:1]
	s_mov_b64 s[0:1], 0x12200000
	v_lshrrev_b32_e32 v89, 3, v212
	v_lshl_add_u64 v[84:85], v[0:1], 0, s[0:1]
	v_xor_b32_e32 v0, v89, v212
	v_lshlrev_b32_e32 v0, 4, v0
	v_lshrrev_b32_e32 v2, 2, v212
	v_and_b32_e32 v0, 0x70, v0
	v_add_u32_e32 v93, 0, v0
	v_bitop3_b32 v0, v2, v3, 4 bitop3:0x6c
	v_mbcnt_lo_u32_b32 v10, -1, 0
	v_lshl_add_u32 v100, v0, 4, 0
	v_add_u32_e32 v0, 0x200, v212
	v_mbcnt_hi_u32_b32 v10, -1, v10
	v_lshrrev_b32_e32 v101, 3, v0
	v_lshrrev_b32_e32 v0, 2, v0
	v_bfe_u32 v9, v212, 5, 1
	v_and_b32_e32 v12, 64, v10
	v_bitop3_b32 v0, v0, v3, 4 bitop3:0x6c
	v_lshlrev_b32_e32 v107, 2, v9
	v_xor_b32_e32 v11, 32, v10
	v_add_u32_e32 v12, 64, v12
	v_lshl_add_u32 v5, v0, 4, 0
	v_add_u32_e32 v0, 0x600, v212
	v_cmp_lt_i32_e32 vcc, v11, v12
	v_and_or_b32 v109, v2, 3, v107
	v_bfe_u32 v2, v212, 1, 1
	v_lshrrev_b32_e32 v104, 3, v0
	v_cndmask_b32_e32 v10, v10, v11, vcc
	v_and_or_b32 v110, v89, 2, v2
	v_lshlrev_b32_e32 v2, 3, v212
	v_xor_b32_e32 v4, v101, v212
	v_xor_b32_e32 v7, v104, v212
	v_lshlrev_b32_e32 v108, 2, v10
	v_and_b32_e32 v10, 8, v2
	v_and_b32_e32 v113, 56, v2
	v_bitop3_b32 v2, v9, v212, 7 bitop3:0x78
	v_lshlrev_b32_e32 v4, 4, v4
	v_lshlrev_b32_e32 v7, 4, v7
	v_lshrrev_b32_e32 v0, 2, v0
	v_lshlrev_b32_e32 v115, 4, v2
	v_bitop3_b32 v2, v9, v3, 2 bitop3:0x36
	v_and_b32_e32 v4, 0x70, v4
	v_and_b32_e32 v7, 0x70, v7
	v_bitop3_b32 v0, v0, v3, 4 bitop3:0x6c
	v_bfe_u32 v86, v212, 3, 3
	v_lshlrev_b32_e32 v116, 4, v2
	v_bitop3_b32 v2, v9, v3, 4 bitop3:0x36
	s_add_u32 s12, s80, 0x1a200000
	v_and_b32_e32 v87, 31, v212
	v_lshlrev_b32_e32 v1, 7, v101
	v_add_u32_e32 v4, 0, v4
	v_or_b32_e32 v102, 0x80, v89
	v_lshlrev_b32_e32 v6, 7, v104
	v_add_u32_e32 v7, 0, v7
	v_lshl_add_u32 v8, v0, 4, 0
	v_lshlrev_b32_e32 v0, 3, v9
	v_add_u32_e32 v111, 0, v10
	v_readlane_b32 s0, v255, 27
	v_lshlrev_b32_e32 v10, 4, v9
	v_lshlrev_b32_e32 v117, 4, v2
	v_bitop3_b32 v2, v9, v3, 6 bitop3:0x36
	v_or_b32_e32 v88, 8, v86
	v_or_b32_e32 v90, 16, v86
	v_or_b32_e32 v92, 24, v86
	s_addc_u32 s13, s81, 0
	v_lshlrev_b32_e32 v91, 7, v89
	v_lshlrev_b32_e32 v103, 7, v102
	v_lshlrev_b32_e32 v105, 6, v87
	v_lshl_add_u32 v106, v87, 7, 0
	v_lshl_add_u32 v112, v87, 2, s0
	v_lshlrev_b32_e32 v114, 8, v86
	v_lshlrev_b32_e32 v118, 4, v2
	v_cmp_gt_u32_e64 s[2:3], v107, v87
	v_cmp_ge_u32_e64 s[4:5], v107, v87
	v_or_b32_e32 v119, 4, v110
	v_lshlrev_b32_e32 v120, 10, v9
	v_lshlrev_b32_e32 v121, 8, v88
	v_lshlrev_b32_e32 v122, 8, v90
	v_lshlrev_b32_e32 v123, 8, v92
	v_add_u32_e32 v124, v4, v1
	v_add_u32_e32 v125, v5, v1
	v_add_u32_e32 v126, v7, v6
	v_add_u32_e32 v127, v8, v6
	v_lshlrev_b32_e32 v94, 1, v0
	v_add_u32_e32 v128, s0, v10
	v_mov_b32_e32 v129, 0xf149f2ca
	s_mov_b32 s17, s84
	s_branch .LBB0_652

.LBB0_718:
	s_cmp_lt_i32 s62, 8
	s_cselect_b64 s[0:1], -1, 0
	s_cmp_gt_i32 s63, 7
	s_cselect_b64 s[2:3], -1, 0
	s_and_b64 s[0:1], s[0:1], s[2:3]
	s_andn2_b64 vcc, exec, s[0:1]
	s_cbranch_vccnz .LBB0_797
	v_readfirstlane_b32 s0, v212
	s_cmp_lt_u32 s0, 0x100
	s_cbranch_scc1 .Lmy_gpr_7
	s_setprio 1

.LBB0_797:
	s_setprio 0
	s_add_u32 s48, s80, 0xe00000
	s_addc_u32 s49, s81, 0
	s_cmp_lt_i32 s62, 9
	s_cselect_b64 s[0:1], -1, 0
	s_cmp_gt_i32 s63, 8
	s_cselect_b64 s[2:3], -1, 0
	s_and_b64 s[0:1], s[0:1], s[2:3]
	s_andn2_b64 vcc, exec, s[0:1]
	s_cbranch_vccnz .LBB0_875
	v_mov_b32_e32 v0, v212
	s_mov_b32 s0, 0x8000
	s_nop 0
	v_cmp_gt_i32_e32 vcc, s0, v0
	s_and_saveexec_b64 s[0:1], vcc
	s_cbranch_execz .LBB0_810
	s_waitcnt lgkmcnt(0)
	v_and_b32_e32 v9, 15, v0
	v_lshrrev_b32_e32 v1, 4, v0
	v_lshl_add_u32 v8, v9, 13, 0
	v_lshl_add_u32 v10, v1, 2, v8
	v_mul_u32_u24_e32 v11, 0x8040, v1
	v_lshl_add_u32 v11, v9, 2, v11
	v_add_u32_e32 v11, 0x6000, v11
	s_mov_b64 s[2:3], s[70:71]
	global_load_dword v140, v11, s[2:3]
	s_add_u32 s2, s2, 0x100800
	s_addc_u32 s3, s3, 0
	global_load_dword v141, v11, s[2:3]
	s_add_u32 s2, s2, 0x100800
	s_addc_u32 s3, s3, 0
	global_load_dword v142, v11, s[2:3]
	s_add_u32 s2, s2, 0x100800
	s_addc_u32 s3, s3, 0
	global_load_dword v143, v11, s[2:3]
	s_add_u32 s2, s2, 0x100800
	s_addc_u32 s3, s3, 0
	global_load_dword v144, v11, s[2:3]
	s_add_u32 s2, s2, 0x100800
	s_addc_u32 s3, s3, 0
	global_load_dword v145, v11, s[2:3]
	s_add_u32 s2, s2, 0x100800
	s_addc_u32 s3, s3, 0
	global_load_dword v146, v11, s[2:3]
	s_add_u32 s2, s2, 0x100800
	s_addc_u32 s3, s3, 0
	global_load_dword v147, v11, s[2:3]
	s_add_u32 s2, s2, 0x100800
	s_addc_u32 s3, s3, 0
	global_load_dword v148, v11, s[2:3]
	s_add_u32 s2, s2, 0x100800
	s_addc_u32 s3, s3, 0
	global_load_dword v149, v11, s[2:3]
	s_add_u32 s2, s2, 0x100800
	s_addc_u32 s3, s3, 0
	global_load_dword v150, v11, s[2:3]
	s_add_u32 s2, s2, 0x100800
	s_addc_u32 s3, s3, 0
	global_load_dword v151, v11, s[2:3]
	s_add_u32 s2, s2, 0x100800
	s_addc_u32 s3, s3, 0
	global_load_dword v152, v11, s[2:3]
	s_add_u32 s2, s2, 0x100800
	s_addc_u32 s3, s3, 0
	global_load_dword v153, v11, s[2:3]
	s_add_u32 s2, s2, 0x100800
	s_addc_u32 s3, s3, 0
	global_load_dword v154, v11, s[2:3]
	s_add_u32 s2, s2, 0x100800
	s_addc_u32 s3, s3, 0
	global_load_dword v155, v11, s[2:3]
	s_add_u32 s2, s2, 0x100800
	s_addc_u32 s3, s3, 0
	global_load_dword v156, v11, s[2:3]
	s_add_u32 s2, s2, 0x100800
	s_addc_u32 s3, s3, 0
	global_load_dword v157, v11, s[2:3]
	s_add_u32 s2, s2, 0x100800
	s_addc_u32 s3, s3, 0
	global_load_dword v158, v11, s[2:3]
	s_add_u32 s2, s2, 0x100800
	s_addc_u32 s3, s3, 0
	global_load_dword v159, v11, s[2:3]
	s_add_u32 s2, s2, 0x100800
	s_addc_u32 s3, s3, 0
	global_load_dword v160, v11, s[2:3]
	s_add_u32 s2, s2, 0x100800
	s_addc_u32 s3, s3, 0
	global_load_dword v161, v11, s[2:3]
	s_add_u32 s2, s2, 0x100800
	s_addc_u32 s3, s3, 0
	global_load_dword v162, v11, s[2:3]
	s_add_u32 s2, s2, 0x100800
	s_addc_u32 s3, s3, 0
	global_load_dword v163, v11, s[2:3]
	s_add_u32 s2, s2, 0x100800
	s_addc_u32 s3, s3, 0
	global_load_dword v164, v11, s[2:3]
	s_add_u32 s2, s2, 0x100800
	s_addc_u32 s3, s3, 0
	global_load_dword v165, v11, s[2:3]
	s_add_u32 s2, s2, 0x100800
	s_addc_u32 s3, s3, 0
	global_load_dword v166, v11, s[2:3]
	s_add_u32 s2, s2, 0x100800
	s_addc_u32 s3, s3, 0
	global_load_dword v167, v11, s[2:3]
	s_add_u32 s2, s2, 0x100800
	s_addc_u32 s3, s3, 0
	global_load_dword v168, v11, s[2:3]
	s_add_u32 s2, s2, 0x100800
	s_addc_u32 s3, s3, 0
	global_load_dword v169, v11, s[2:3]
	s_add_u32 s2, s2, 0x100800
	s_addc_u32 s3, s3, 0
	global_load_dword v170, v11, s[2:3]
	s_add_u32 s2, s2, 0x100800
	s_addc_u32 s3, s3, 0
	global_load_dword v171, v11, s[2:3]
	s_add_u32 s2, s2, 0x100800
	s_addc_u32 s3, s3, 0
	global_load_dword v172, v11, s[2:3]
	s_add_u32 s2, s2, 0x100800
	s_addc_u32 s3, s3, 0
	global_load_dword v173, v11, s[2:3]
	s_add_u32 s2, s2, 0x100800
	s_addc_u32 s3, s3, 0
	global_load_dword v174, v11, s[2:3]
	s_add_u32 s2, s2, 0x100800
	s_addc_u32 s3, s3, 0
	global_load_dword v175, v11, s[2:3]
	s_add_u32 s2, s2, 0x100800
	s_addc_u32 s3, s3, 0
	global_load_dword v176, v11, s[2:3]
	s_add_u32 s2, s2, 0x100800
	s_addc_u32 s3, s3, 0
	global_load_dword v177, v11, s[2:3]
	s_add_u32 s2, s2, 0x100800
	s_addc_u32 s3, s3, 0
	global_load_dword v178, v11, s[2:3]
	s_add_u32 s2, s2, 0x100800
	s_addc_u32 s3, s3, 0
	global_load_dword v179, v11, s[2:3]
	s_add_u32 s2, s2, 0x100800
	s_addc_u32 s3, s3, 0
	global_load_dword v180, v11, s[2:3]
	s_add_u32 s2, s2, 0x100800
	s_addc_u32 s3, s3, 0
	global_load_dword v181, v11, s[2:3]
	s_add_u32 s2, s2, 0x100800
	s_addc_u32 s3, s3, 0
	global_load_dword v182, v11, s[2:3]
	s_add_u32 s2, s2, 0x100800
	s_addc_u32 s3, s3, 0
	global_load_dword v183, v11, s[2:3]
	s_add_u32 s2, s2, 0x100800
	s_addc_u32 s3, s3, 0
	global_load_dword v184, v11, s[2:3]
	s_add_u32 s2, s2, 0x100800
	s_addc_u32 s3, s3, 0
	global_load_dword v185, v11, s[2:3]
	s_add_u32 s2, s2, 0x100800
	s_addc_u32 s3, s3, 0
	global_load_dword v186, v11, s[2:3]
	s_add_u32 s2, s2, 0x100800
	s_addc_u32 s3, s3, 0
	global_load_dword v187, v11, s[2:3]
	s_add_u32 s2, s2, 0x100800
	s_addc_u32 s3, s3, 0
	global_load_dword v188, v11, s[2:3]
	s_add_u32 s2, s2, 0x100800
	s_addc_u32 s3, s3, 0
	global_load_dword v189, v11, s[2:3]
	s_add_u32 s2, s2, 0x100800
	s_addc_u32 s3, s3, 0
	global_load_dword v190, v11, s[2:3]
	s_add_u32 s2, s2, 0x100800
	s_addc_u32 s3, s3, 0
	global_load_dword v191, v11, s[2:3]
	s_add_u32 s2, s2, 0x100800
	s_addc_u32 s3, s3, 0
	global_load_dword v192, v11, s[2:3]
	s_add_u32 s2, s2, 0x100800
	s_addc_u32 s3, s3, 0
	global_load_dword v193, v11, s[2:3]
	s_add_u32 s2, s2, 0x100800
	s_addc_u32 s3, s3, 0
	global_load_dword v194, v11, s[2:3]
	s_add_u32 s2, s2, 0x100800
	s_addc_u32 s3, s3, 0
	global_load_dword v195, v11, s[2:3]
	s_add_u32 s2, s2, 0x100800
	s_addc_u32 s3, s3, 0
	global_load_dword v196, v11, s[2:3]
	s_add_u32 s2, s2, 0x100800
	s_addc_u32 s3, s3, 0
	global_load_dword v197, v11, s[2:3]
	s_add_u32 s2, s2, 0x100800
	s_addc_u32 s3, s3, 0
	global_load_dword v198, v11, s[2:3]
	s_add_u32 s2, s2, 0x100800
	s_addc_u32 s3, s3, 0
	global_load_dword v199, v11, s[2:3]
	s_add_u32 s2, s2, 0x100800
	s_addc_u32 s3, s3, 0
	global_load_dword v200, v11, s[2:3]
	s_add_u32 s2, s2, 0x100800
	s_addc_u32 s3, s3, 0
	global_load_dword v201, v11, s[2:3]
	s_add_u32 s2, s2, 0x100800
	s_addc_u32 s3, s3, 0
	global_load_dword v202, v11, s[2:3]
	s_add_u32 s2, s2, 0x100800
	s_addc_u32 s3, s3, 0
	global_load_dword v203, v11, s[2:3]
	s_waitcnt vmcnt(48)
	ds_write_b32 v10, v140
	ds_write_b32 v10, v141 offset:128
	ds_write_b32 v10, v142 offset:256
	ds_write_b32 v10, v143 offset:384
	ds_write_b32 v10, v144 offset:512
	ds_write_b32 v10, v145 offset:640
	ds_write_b32 v10, v146 offset:768
	ds_write_b32 v10, v147 offset:896
	ds_write_b32 v10, v148 offset:1024
	ds_write_b32 v10, v149 offset:1152
	ds_write_b32 v10, v150 offset:1280
	ds_write_b32 v10, v151 offset:1408
	ds_write_b32 v10, v152 offset:1536
	ds_write_b32 v10, v153 offset:1664
	ds_write_b32 v10, v154 offset:1792
	ds_write_b32 v10, v155 offset:1920
	s_waitcnt vmcnt(32)
	ds_write_b32 v10, v156 offset:2048
	ds_write_b32 v10, v157 offset:2176
	ds_write_b32 v10, v158 offset:2304
	ds_write_b32 v10, v159 offset:2432
	ds_write_b32 v10, v160 offset:2560
	ds_write_b32 v10, v161 offset:2688
	ds_write_b32 v10, v162 offset:2816
	ds_write_b32 v10, v163 offset:2944
	ds_write_b32 v10, v164 offset:3072
	ds_write_b32 v10, v165 offset:3200
	ds_write_b32 v10, v166 offset:3328
	ds_write_b32 v10, v167 offset:3456
	ds_write_b32 v10, v168 offset:3584
	ds_write_b32 v10, v169 offset:3712
	ds_write_b32 v10, v170 offset:3840
	ds_write_b32 v10, v171 offset:3968
	s_waitcnt vmcnt(16)
	ds_write_b32 v10, v172 offset:4096
	ds_write_b32 v10, v173 offset:4224
	ds_write_b32 v10, v174 offset:4352
	ds_write_b32 v10, v175 offset:4480
	ds_write_b32 v10, v176 offset:4608
	ds_write_b32 v10, v177 offset:4736
	ds_write_b32 v10, v178 offset:4864
	ds_write_b32 v10, v179 offset:4992
	ds_write_b32 v10, v180 offset:5120
	ds_write_b32 v10, v181 offset:5248
	ds_write_b32 v10, v182 offset:5376
	ds_write_b32 v10, v183 offset:5504
	ds_write_b32 v10, v184 offset:5632
	ds_write_b32 v10, v185 offset:5760
	ds_write_b32 v10, v186 offset:5888
	ds_write_b32 v10, v187 offset:6016
	s_waitcnt vmcnt(0)
	ds_write_b32 v10, v188 offset:6144
	ds_write_b32 v10, v189 offset:6272
	ds_write_b32 v10, v190 offset:6400
	ds_write_b32 v10, v191 offset:6528
	ds_write_b32 v10, v192 offset:6656
	ds_write_b32 v10, v193 offset:6784
	ds_write_b32 v10, v194 offset:6912
	ds_write_b32 v10, v195 offset:7040
	ds_write_b32 v10, v196 offset:7168
	ds_write_b32 v10, v197 offset:7296
	ds_write_b32 v10, v198 offset:7424
	ds_write_b32 v10, v199 offset:7552
	ds_write_b32 v10, v200 offset:7680
	ds_write_b32 v10, v201 offset:7808
	ds_write_b32 v10, v202 offset:7936
	ds_write_b32 v10, v203 offset:8064

.LBB0_875:
	s_cmp_lt_i32 s62, 10
	s_cselect_b64 s[0:1], -1, 0
	s_cmp_gt_i32 s63, 9
	s_cselect_b64 s[2:3], -1, 0
	s_and_b64 s[0:1], s[0:1], s[2:3]
	s_andn2_b64 vcc, exec, s[0:1]
	s_cbranch_vccnz .LBB0_1044
	v_readfirstlane_b32 s0, v212
	s_cmp_lt_u32 s0, 0x100
	s_cbranch_scc1 .Lmy_gpr_9
	s_setprio 1
.Lmy_gpr_9:
	s_cmp_lt_i32 s84, 16
	s_cselect_b64 s[0:1], -1, 0
	s_cmp_lt_u32 s85, 64
	s_cselect_b64 s[2:3], -1, 0
	s_and_b64 s[0:1], s[0:1], s[2:3]
	v_mov_b32_e32 v0, v212
	s_andn2_b64 vcc, exec, s[0:1]
	s_cbranch_vccnz .LBB0_889
	s_lshl_b32 s0, s84, 7
	v_and_b32_e32 v0, 63, v0
	s_add_i32 s1, s0, 0x62000
	v_or_b32_e32 v2, s1, v0
	s_waitcnt lgkmcnt(0)
	v_ashrrev_i32_e32 v3, 31, v2
	s_add_i32 s1, s0, 0x62040
	v_lshl_add_u64 v[6:7], v[2:3], 2, s[48:49]
	v_or_b32_e32 v2, s1, v0
	v_ashrrev_i32_e32 v3, 31, v2
	s_add_i32 s1, s0, 0x63000
	v_lshl_add_u64 v[8:9], v[2:3], 2, s[48:49]
	v_or_b32_e32 v2, s1, v0
	v_ashrrev_i32_e32 v3, 31, v2
	s_add_i32 s0, s0, 0x63040
	v_lshl_add_u64 v[10:11], v[2:3], 2, s[48:49]
	v_or_b32_e32 v2, s0, v0
	v_ashrrev_i32_e32 v3, 31, v2
	v_lshl_add_u64 v[12:13], v[2:3], 2, s[48:49]
	global_load_dword v1, v[6:7], off
	global_load_dword v2, v[8:9], off
	global_load_dword v3, v[10:11], off
	global_load_dword v4, v[12:13], off
	s_lshl_b32 s5, s84, 4
	s_mov_b32 s11, 0
	v_cmp_ne_u32_e32 vcc, 0, v0
	v_cmp_eq_u32_e64 s[0:1], 0, v0
	s_mul_i32 s4, s84, 0x81
	s_add_i32 s5, s5, 0x61000
	v_mov_b32_e32 v5, 0
	v_mov_b32_e32 v8, 0
	v_mov_b32_e32 v9, 0
	s_mov_b32 s8, 0x3fb8aa3b
	s_mov_b32 s9, 0xc2ce8ed0
	s_mov_b32 s10, 0x42b17218
	v_mov_b32_e32 v6, 0x7f800000
	v_mov_b32_e32 v7, 0
	s_waitcnt vmcnt(0)

.LBB0_1044:
	s_setprio 0
	s_cmp_lt_i32 s62, 11
	s_cselect_b64 s[0:1], -1, 0
	s_cmp_gt_i32 s63, 10
	s_cselect_b64 s[2:3], -1, 0
	s_and_b64 s[0:1], s[0:1], s[2:3]
	s_andn2_b64 vcc, exec, s[0:1]
	s_cbranch_vccnz .LBB0_1118
	v_mov_b32_e32 v0, v212
	s_cmpk_gt_i32 s84, 0xff
	s_cbranch_scc1 .LBB0_1064
	s_add_u32 s17, s80, 0x10200000
	s_addc_u32 s28, s81, 0
	s_add_u32 s29, s80, 0x12200000
	s_addc_u32 s30, s81, 0
	s_add_u32 s31, s80, 0x1000000
	s_addc_u32 s33, s81, 0
	s_add_u32 s34, s80, 0x3000000
	s_addc_u32 s35, s81, 0
	s_add_u32 s36, s80, 0xe80000
	s_addc_u32 s37, s81, 0
	s_add_u32 s38, s80, 0xf00000
	s_addc_u32 s39, s81, 0
	s_add_u32 s40, s80, 0xf80000
	v_mbcnt_lo_u32_b32 v0, -1, 0
	s_addc_u32 s41, s81, 0
	s_movk_i32 s42, 0x80
	s_mov_b32 s1, 0
	v_mov_b32_e32 v65, 0
	s_add_i32 s43, 0, 0x10000
	s_add_i32 s44, 0, 0x1a000
	s_add_i32 s45, 0, 0x1a100
	s_add_i32 s46, 0, 0x1a200
	s_add_i32 s47, 0, 0x1a300
	s_add_i32 s52, 0, 0x4000
	s_add_i32 s53, 0, 0x4400
	s_movk_i32 s54, 0x1000
	s_movk_i32 s55, 0x2000
	s_movk_i32 s56, 0x3000
	s_add_i32 s57, 0, 0x1a700
	v_mov_b32_e32 v73, 0x80
	v_mov_b32_e32 v76, 0x90
	v_mov_b32_e32 v77, 0xa0
	v_mov_b32_e32 v78, 0xb0
	v_mov_b32_e32 v79, 0xc0
	v_mov_b32_e32 v80, 0xd0
	v_mov_b32_e32 v81, 0xe0
	v_mov_b32_e32 v82, 0xf0
	v_mbcnt_hi_u32_b32 v83, -1, v0
	s_mov_b32 s8, s84
	s_branch .LBB0_1048

.LBB0_1326:
	s_cmp_lt_i32 s62, 15
	s_cselect_b64 s[0:1], -1, 0
	s_cmp_gt_i32 s63, 14
	s_cselect_b64 s[2:3], -1, 0
	s_and_b64 s[0:1], s[0:1], s[2:3]
	s_andn2_b64 vcc, exec, s[0:1]
	s_waitcnt lgkmcnt(0)
	v_readlane_b32 s74, v255, 23
	v_readlane_b32 s75, v255, 24
	s_cbranch_vccnz .LBB0_1405
	v_readfirstlane_b32 s0, v212
	s_cmp_lt_u32 s0, 0x100
	s_cbranch_scc1 .Lmy_gpr_14
	s_setprio 1
.Lmy_gpr_14:
	v_mov_b32_e32 v0, v212
	s_waitcnt vmcnt(0)
	s_cmpk_gt_i32 s93, 0x1ff
	v_readfirstlane_b32 s3, v212
	s_cbranch_scc1 .LBB0_1351
	s_ashr_i32 s24, s93, 31
	s_lshr_b32 s0, s24, 29
	s_add_i32 s4, s93, s0
	s_and_b32 s0, s4, -8
	s_sub_i32 s5, s93, s0
	s_cmp_gt_i32 s5, -1
	s_cbranch_scc0 .LBB0_1330
	s_lshl_b32 s2, s5, 6
	s_cbranch_execz .LBB0_1331
	s_branch .LBB0_1332

.LBB0_1405:
	s_setprio 0
	s_cmp_lt_i32 s62, 16
	s_cselect_b64 s[0:1], -1, 0
	s_cmp_gt_i32 s63, 15
	s_cselect_b64 s[2:3], -1, 0
	s_and_b64 s[0:1], s[0:1], s[2:3]
	s_andn2_b64 vcc, exec, s[0:1]
	s_cbranch_vccnz .LBB0_1463
	v_readlane_b32 s0, v255, 25
	v_mov_b32_e32 v0, v212
	s_cmpk_gt_i32 s0, 0x3fff
	v_readlane_b32 s1, v255, 26
	s_cbranch_scc1 .LBB0_1409
	v_and_b32_e32 v4, 63, v0
	v_mbcnt_lo_u32_b32 v0, -1, 0
	v_mbcnt_hi_u32_b32 v0, -1, v0
	v_and_b32_e32 v1, 64, v0
	v_add_u32_e32 v1, 64, v1
	v_xor_b32_e32 v2, 1, v0
	v_cmp_lt_i32_e32 vcc, v2, v1
	v_readlane_b32 s0, v255, 7
	v_readlane_b32 s1, v255, 8
	v_cndmask_b32_e32 v2, v0, v2, vcc
	v_lshlrev_b32_e32 v26, 2, v2
	v_xor_b32_e32 v2, 2, v0
	v_cmp_lt_i32_e32 vcc, v2, v1
	v_readlane_b32 s4, v255, 11
	v_readlane_b32 s5, v255, 12
	v_cndmask_b32_e32 v2, v0, v2, vcc
	v_lshlrev_b32_e32 v27, 2, v2
	v_xor_b32_e32 v2, 4, v0
	v_cmp_lt_i32_e32 vcc, v2, v1
	s_mov_b64 s[0:1], 0x6000
	v_readlane_b32 s8, v255, 15
	v_cndmask_b32_e32 v2, v0, v2, vcc
	v_lshlrev_b32_e32 v28, 2, v2
	v_xor_b32_e32 v2, 8, v0
	v_cmp_lt_i32_e32 vcc, v2, v1
	v_readlane_b32 s9, v255, 16
	v_readlane_b32 s2, v255, 9
	v_cndmask_b32_e32 v2, v0, v2, vcc
	v_lshlrev_b32_e32 v29, 2, v2
	v_xor_b32_e32 v2, 16, v0
	v_cmp_lt_i32_e32 vcc, v2, v1
	v_readlane_b32 s3, v255, 10
	v_readlane_b32 s6, v255, 13
	v_cndmask_b32_e32 v2, v0, v2, vcc
	v_lshlrev_b32_e32 v30, 2, v2
	v_xor_b32_e32 v2, 32, v0
	v_cmp_lt_i32_e32 vcc, v2, v1
	v_mov_b32_e32 v1, 0
	v_readlane_b32 s7, v255, 14
	v_cndmask_b32_e32 v0, v0, v2, vcc
	v_lshlrev_b32_e32 v31, 2, v0
	v_lshlrev_b32_e32 v0, 4, v4
	v_lshl_add_u64 v[2:3], s[4:5], 0, v[0:1]
	v_lshl_add_u64 v[12:13], v[2:3], 0, s[0:1]
	s_mov_b64 s[0:1], 0x7000
	v_lshl_add_u64 v[14:15], v[2:3], 0, s[0:1]
	s_mov_b64 s[0:1], 0x7400
	v_lshl_add_u64 v[16:17], v[2:3], 0, s[0:1]
	s_mov_b64 s[0:1], 0x7800
	v_lshl_add_u64 v[18:19], v[2:3], 0, s[0:1]
	s_mov_b64 s[0:1], 0x7c00
	v_lshl_add_u64 v[20:21], v[2:3], 0, s[0:1]
	v_readlane_b32 s0, v255, 25
	v_readlane_b32 s1, v255, 26
	s_mov_b32 s8, s0
	s_ashr_i32 s9, s0, 31
	s_lshl_b64 s[0:1], s[8:9], 13
	s_add_u32 s0, s78, s0
	s_addc_u32 s1, s79, s1
	v_lshl_add_u64 v[2:3], s[0:1], 0, v[0:1]
	s_mov_b64 s[0:1], 0x1000
	s_ashr_i32 s75, s74, 31
	v_lshl_add_u64 v[22:23], v[2:3], 0, s[0:1]
	s_lshl_b64 s[2:3], s[74:75], 13
	s_lshl_b64 s[0:1], s[8:9], 12
	s_add_u32 s0, s80, s0
	v_lshlrev_b32_e32 v0, 3, v4
	s_addc_u32 s1, s81, s1
	v_lshl_add_u64 v[0:1], s[0:1], 0, v[0:1]
	s_mov_b64 s[0:1], 0xa200000
	v_lshl_add_u64 v[24:25], v[0:1], 0, s[0:1]
	s_mov_b32 s0, s8
	v_readlane_b32 s10, v255, 17
	v_readlane_b32 s11, v255, 18
	v_readlane_b32 s12, v255, 19
	v_readlane_b32 s13, v255, 20
	v_readlane_b32 s14, v255, 21
	v_readlane_b32 s15, v255, 22
	v_writelane_b32 v255, s0, 25
	s_lshl_b64 s[4:5], s[74:75], 12
	v_mov_b32_e32 v32, 0x358637bd
	s_mov_b32 s6, 0xf800000
	v_mov_b32_e32 v33, 0x260
	v_writelane_b32 v255, s1, 26
	s_mov_b32 s7, s8
	global_load_dwordx4 v[132:135], v[12:13], off offset:1024
	global_load_dwordx4 v[136:139], v[12:13], off offset:2048
	global_load_dwordx4 v[140:143], v[12:13], off offset:3072
	global_load_dwordx4 v[144:147], v[14:15], off
	global_load_dwordx4 v[148:151], v[16:17], off
	global_load_dwordx4 v[152:155], v[18:19], off
	global_load_dwordx4 v[156:159], v[20:21], off

.LBB0_1463:
	s_cmp_lt_i32 s62, 17
	s_cselect_b64 s[0:1], -1, 0
	s_cmp_gt_i32 s63, 16
	s_cselect_b64 s[2:3], -1, 0
	s_and_b64 s[0:1], s[0:1], s[2:3]
	s_andn2_b64 vcc, exec, s[0:1]
	s_cbranch_vccnz .LBB0_1587
	v_readfirstlane_b32 s0, v212
	s_cmp_lt_u32 s0, 0x100
	s_cbranch_scc1 .Lmy_gpr_16
	s_setprio 1

.LBB0_1587:
	s_setprio 0
	s_cmp_lt_i32 s62, 18
	s_cselect_b64 s[0:1], -1, 0
	s_cmp_gt_i32 s63, 17
	s_cselect_b64 s[2:3], -1, 0
	s_and_b64 s[0:1], s[0:1], s[2:3]
	s_andn2_b64 vcc, exec, s[0:1]
	s_cbranch_vccnz .LBB0_1680
	v_mov_b32_e32 v0, v212
	v_readlane_b32 s0, v255, 7
	v_and_b32_e32 v0, 63, v0
	v_lshlrev_b32_e32 v0, 2, v0
	v_readlane_b32 s12, v255, 19
	v_readlane_b32 s13, v255, 20
	s_nop 4
	global_load_dword v1, v0, s[12:13] offset:2816
	global_load_dword v2, v0, s[12:13] offset:3072
	global_load_dword v3, v0, s[12:13] offset:3840
	global_load_dword v4, v0, s[12:13] offset:3328
	global_load_dword v5, v0, s[12:13] offset:2304
	global_load_dword v6, v0, s[12:13] offset:2560
	global_load_dword v7, v0, s[12:13] offset:2048
	global_load_dword v8, v0, s[12:13] offset:3584
	v_mbcnt_lo_u32_b32 v0, -1, 0
	v_mbcnt_hi_u32_b32 v0, -1, v0
	v_and_b32_e32 v9, 64, v0
	v_xor_b32_e32 v10, 1, v0
	v_add_u32_e32 v9, 64, v9
	v_cmp_lt_i32_e32 vcc, v10, v9
	v_xor_b32_e32 v11, 2, v0
	v_xor_b32_e32 v12, 4, v0
	v_cndmask_b32_e32 v10, v0, v10, vcc
	v_lshlrev_b32_e32 v213, 2, v10
	v_cmp_lt_i32_e32 vcc, v11, v9
	v_xor_b32_e32 v13, 8, v0
	v_xor_b32_e32 v14, 16, v0
	v_xor_b32_e32 v15, 32, v0
	v_readlane_b32 s5, v255, 12
	s_cmpk_gt_i32 s84, 0x3ff
	s_mov_b32 s5, 0
	v_readlane_b32 s1, v255, 8
	v_readlane_b32 s2, v255, 9
	v_readlane_b32 s3, v255, 10
	v_readlane_b32 s4, v255, 11
	v_readlane_b32 s6, v255, 13
	v_readlane_b32 s7, v255, 14
	v_readlane_b32 s8, v255, 15
	v_readlane_b32 s9, v255, 16
	v_readlane_b32 s10, v255, 17
	v_readlane_b32 s11, v255, 18
	v_readlane_b32 s14, v255, 21
	v_readlane_b32 s15, v255, 22
	s_waitcnt vmcnt(0)
	v_mul_f32_e32 v3, v4, v3
	v_mul_f32_e32 v1, v5, v1
	v_cndmask_b32_e32 v5, v0, v11, vcc
	v_fmac_f32_e32 v1, v7, v6
	v_fmac_f32_e32 v3, v2, v8
	ds_bpermute_b32 v2, v213, v1
	ds_bpermute_b32 v4, v213, v3
	v_lshlrev_b32_e32 v214, 2, v5
	v_cmp_lt_i32_e32 vcc, v12, v9
	s_waitcnt lgkmcnt(0)
	v_add_f32_e32 v1, v1, v2
	v_add_f32_e32 v2, v3, v4
	ds_bpermute_b32 v3, v214, v1
	ds_bpermute_b32 v4, v214, v2
	v_cndmask_b32_e32 v5, v0, v12, vcc
	v_lshlrev_b32_e32 v215, 2, v5
	v_cmp_lt_i32_e32 vcc, v13, v9
	s_waitcnt lgkmcnt(1)
	v_add_f32_e32 v1, v1, v3
	s_waitcnt lgkmcnt(0)
	v_add_f32_e32 v2, v2, v4
	ds_bpermute_b32 v3, v215, v1
	ds_bpermute_b32 v4, v215, v2
	v_cndmask_b32_e32 v5, v0, v13, vcc
	v_lshlrev_b32_e32 v216, 2, v5
	v_cmp_lt_i32_e32 vcc, v14, v9
	s_waitcnt lgkmcnt(1)
	v_add_f32_e32 v1, v1, v3
	s_waitcnt lgkmcnt(0)
	v_add_f32_e32 v2, v2, v4
	ds_bpermute_b32 v3, v216, v1
	ds_bpermute_b32 v4, v216, v2
	v_cndmask_b32_e32 v5, v0, v14, vcc
	v_lshlrev_b32_e32 v217, 2, v5
	v_cmp_lt_i32_e32 vcc, v15, v9
	s_waitcnt lgkmcnt(1)
	v_add_f32_e32 v1, v1, v3
	s_waitcnt lgkmcnt(0)
	v_add_f32_e32 v3, v2, v4
	ds_bpermute_b32 v2, v217, v1
	ds_bpermute_b32 v4, v217, v3
	v_cndmask_b32_e32 v0, v0, v15, vcc
	v_lshlrev_b32_e32 v218, 2, v0
	s_waitcnt lgkmcnt(1)
	v_add_f32_e32 v2, v1, v2
	s_waitcnt lgkmcnt(0)
	v_add_f32_e32 v0, v3, v4
	ds_bpermute_b32 v3, v218, v2
	ds_bpermute_b32 v1, v218, v0
	s_cbranch_scc1 .LBB0_1626
	s_waitcnt lgkmcnt(1)
	v_add_f32_e32 v2, v2, v3
	s_mov_b32 s0, 0x3fb8aa3b
	v_mul_f32_e32 v3, 0x3fb8aa3b, v2
	v_fma_f32 v4, v2, s0, -v3
	v_rndne_f32_e32 v5, v3
	v_fmac_f32_e32 v4, 0x32a5705f, v2
	v_sub_f32_e32 v3, v3, v5
	v_add_f32_e32 v3, v3, v4
	v_exp_f32_e32 v3, v3
	v_cvt_i32_f32_e32 v4, v5
	s_waitcnt lgkmcnt(0)
	v_add_f32_e32 v0, v0, v1
	s_mov_b32 s1, 0xc2ce8ed0
	v_cmp_ngt_f32_e32 vcc, s1, v2
	v_ldexp_f32 v1, v3, v4
	v_mul_f32_e32 v3, 0x3fb8aa3b, v0
	v_fma_f32 v4, v0, s0, -v3
	v_rndne_f32_e32 v5, v3
	v_fmac_f32_e32 v4, 0x32a5705f, v0
	v_sub_f32_e32 v3, v3, v5
	v_add_f32_e32 v3, v3, v4
	v_exp_f32_e32 v3, v3
	v_cvt_i32_f32_e32 v4, v5
	s_mov_b32 s2, 0x42b17218
	v_cndmask_b32_e32 v1, 0, v1, vcc
	v_mov_b32_e32 v5, 0x7f800000
	v_cmp_nlt_f32_e32 vcc, s2, v2
	v_ldexp_f32 v2, v3, v4
	v_bfe_u32 v222, v212, 5, 1
	v_cndmask_b32_e32 v1, v5, v1, vcc
	v_cmp_ngt_f32_e32 vcc, s1, v0
	v_bfe_u32 v3, v212, 2, 2
	v_lshlrev_b32_e32 v223, 2, v222
	v_cndmask_b32_e32 v2, 0, v2, vcc
	v_cmp_nlt_f32_e32 vcc, s2, v0
	v_lshrrev_b32_e32 v6, 3, v212
	v_and_b32_e32 v221, 31, v212
	v_cndmask_b32_e32 v0, v5, v2, vcc
	v_or_b32_e32 v5, v223, v3
	v_lshlrev_b32_e32 v3, 2, v3
	v_and_b32_e32 v6, 2, v6
	v_bfe_u32 v7, v212, 1, 1
	s_add_u32 s18, s80, 0x12200000
	v_or3_b32 v3, v3, v6, v7
	v_lshlrev_b32_e32 v6, 3, v212
	v_lshlrev_b32_e32 v5, 9, v5
	v_lshlrev_b32_e32 v194, 2, v221
	v_readlane_b32 s0, v255, 27
	s_addc_u32 s19, s81, 0
	v_and_b32_e32 v6, 8, v6
	v_lshl_or_b32 v3, v3, 4, v5
	v_add_u32_e32 v226, s0, v194
	v_lshl_add_u32 v227, v222, 4, s0
	s_movk_i32 s0, 0x80
	v_sub_f32_e32 v0, v1, v0
	s_add_u32 s20, s80, 0x16200000
	v_bitop3_b32 v229, v3, s0, v6 bitop3:0x36
	s_movk_i32 s0, 0xc0
	v_add_f32_e32 v219, 0x3f0e59d5, v0
	s_addc_u32 s21, s81, 0
	v_lshlrev_b32_e32 v0, 3, v221
	v_mov_b32_e32 v1, 0
	v_bitop3_b32 v230, v3, s0, v6 bitop3:0x36
	s_mov_b64 s[0:1], s[80:81]
	s_mov_b32 s48, s84
	s_mov_b64 s[2:3], s[86:87]
	s_mov_b32 s49, s88
	s_mov_b32 s4, s82
	v_readlane_b32 s80, v255, 7
	v_bitop3_b32 v0, v0, v212, 32 bitop3:0x78
	v_lshlrev_b32_e32 v2, 7, v221
	v_lshlrev_b32_e32 v4, 3, v222
	v_lshlrev_b32_e32 v5, 9, v222
	v_lshlrev_b32_e32 v7, 4, v221
	v_mov_b32_e32 v195, v1
	v_readlane_b32 s81, v255, 8
	v_readlane_b32 s82, v255, 9
	v_readlane_b32 s86, v255, 13
	v_readlane_b32 s87, v255, 14
	v_readlane_b32 s93, v255, 20
	v_readlane_b32 s94, v255, 21
	v_readlane_b32 s95, v255, 22
	v_and_b32_e32 v220, 63, v212
	v_or_b32_e32 v224, v3, v6
	v_add3_u32 v225, 0, v5, v7
	v_bitop3_b32 v228, v3, 64, v6 bitop3:0x36
	s_mov_b32 s82, s4
	s_mov_b64 s[86:87], s[2:3]
	s_mov_b64 s[80:81], s[0:1]
	s_mov_b32 s93, s97
	v_lshl_add_u64 v[196:197], s[94:95], 0, v[194:195]
	v_or_b32_e32 v231, 9, v223
	v_or_b32_e32 v232, 10, v223
	v_or_b32_e32 v233, 11, v223
	v_or_b32_e32 v234, 16, v223
	v_or_b32_e32 v235, 17, v223
	v_or_b32_e32 v236, 18, v223
	v_or_b32_e32 v237, 19, v223
	v_or_b32_e32 v238, 24, v223
	v_or_b32_e32 v239, 25, v223
	v_or_b32_e32 v240, 26, v223
	v_or_b32_e32 v241, 27, v223
	v_or_b32_e32 v242, 0x42, v222
	v_or_b32_e32 v243, 64, v222
	s_mov_b64 s[6:7], 0x200000
	v_lshlrev_b32_e32 v198, 1, v0
	s_mov_b64 s[8:9], 0x2000
	s_mov_b64 s[10:11], 0x202000
	v_lshlrev_b32_e32 v200, 1, v2
	v_lshlrev_b32_e32 v202, 1, v4
	s_mov_b64 s[12:13], 0x4000
	s_mov_b64 s[14:15], 0x204000
	s_add_i32 s22, 0, 0x10000
	s_mov_b32 s23, 0xf149f2ca
	s_mov_b64 s[16:17], 0x6000
	v_mov_b32_e32 v244, 0x358637bd
	s_mov_b32 s24, 0xf800000
	v_mov_b32_e32 v245, 0x260
	s_mov_b32 s25, 0x3ee34c56
	s_mov_b32 s26, 0xa200000
	s_mov_b32 s27, 0x1a202000
	s_mov_b32 s28, 0xa202000
	s_mov_b32 s29, 0x1a204000
	s_mov_b32 s30, 0xa204000
	s_mov_b32 s31, 0x1a206000
	s_mov_b32 s34, 0xa206000
	v_mov_b32_e32 v246, 0xf149f2ca
	v_readlane_b32 s83, v255, 10
	v_readlane_b32 s84, v255, 11
	v_readlane_b32 s85, v255, 12
	v_readlane_b32 s88, v255, 15
	v_readlane_b32 s89, v255, 16
	v_readlane_b32 s90, v255, 17
	v_readlane_b32 s91, v255, 18
	v_readlane_b32 s92, v255, 19
	s_branch .LBB0_1591

.LBB0_1680:
	s_cmp_lt_i32 s62, 19
	s_cselect_b64 s[0:1], -1, 0
	s_cmp_gt_i32 s63, 18
	s_cselect_b64 s[2:3], -1, 0
	s_and_b64 s[0:1], s[0:1], s[2:3]
	s_andn2_b64 vcc, exec, s[0:1]
	s_cbranch_vccnz .LBB0_1759
	v_readfirstlane_b32 s0, v212
	s_cmp_lt_u32 s0, 0x100
	s_cbranch_scc1 .Lmy_gpr_18
	s_setprio 1
.Lmy_gpr_18:
	v_mov_b32_e32 v0, v212
	s_waitcnt vmcnt(0)
	s_cmpk_gt_i32 s93, 0x1ff
	v_readfirstlane_b32 s3, v212
	s_cbranch_scc1 .LBB0_1705
	s_ashr_i32 s24, s93, 31
	s_lshr_b32 s0, s24, 29
	s_add_i32 s5, s93, s0
	s_and_b32 s0, s5, -8
	s_sub_i32 s4, s93, s0
	s_cmp_gt_i32 s4, -1
	s_cbranch_scc0 .LBB0_1684
	s_lshl_b32 s2, s4, 6
	s_ashr_i32 s0, s5, 3
	s_cbranch_execz .LBB0_1685
	s_branch .LBB0_1686

.LBB0_1759:
	s_setprio 0
	s_cmp_lt_i32 s62, 20
	s_cselect_b64 s[0:1], -1, 0
	s_cmp_gt_i32 s63, 19
	s_cselect_b64 s[2:3], -1, 0
	s_and_b64 s[0:1], s[0:1], s[2:3]
	s_andn2_b64 vcc, exec, s[0:1]
	s_cbranch_vccnz .LBB0_1817
	v_readlane_b32 s6, v255, 25
	s_cmpk_gt_i32 s6, 0x3fff
	v_readlane_b32 s7, v255, 26
	s_cbranch_scc1 .LBB0_1763
	s_waitcnt lgkmcnt(0)
	v_mbcnt_lo_u32_b32 v1, -1, 0
	v_mbcnt_hi_u32_b32 v1, -1, v1
	v_and_b32_e32 v2, 64, v1
	v_add_u32_e32 v2, 64, v2
	v_xor_b32_e32 v3, 1, v1
	v_cmp_lt_i32_e32 vcc, v3, v2
	v_and_b32_e32 v0, 63, v212
	v_readlane_b32 s8, v255, 7
	v_cndmask_b32_e32 v3, v1, v3, vcc
	v_lshlrev_b32_e32 v24, 2, v3
	v_xor_b32_e32 v3, 2, v1
	v_cmp_lt_i32_e32 vcc, v3, v2
	v_lshlrev_b32_e32 v0, 4, v0
	v_readlane_b32 s14, v255, 13
	v_cndmask_b32_e32 v3, v1, v3, vcc
	v_lshlrev_b32_e32 v25, 2, v3
	v_xor_b32_e32 v3, 4, v1
	v_cmp_lt_i32_e32 vcc, v3, v2
	v_readlane_b32 s15, v255, 14
	s_mov_b64 s[2:3], 0x1400
	v_cndmask_b32_e32 v3, v1, v3, vcc
	v_lshlrev_b32_e32 v26, 2, v3
	v_xor_b32_e32 v3, 8, v1
	v_cmp_lt_i32_e32 vcc, v3, v2
	s_ashr_i32 s7, s6, 31
	s_mov_b64 s[0:1], 0x1000
	v_cndmask_b32_e32 v3, v1, v3, vcc
	v_lshlrev_b32_e32 v27, 2, v3
	v_xor_b32_e32 v3, 16, v1
	v_cmp_lt_i32_e32 vcc, v3, v2
	v_mov_b32_e32 v30, 0x358637bd
	s_mov_b32 s4, 0xf800000
	v_cndmask_b32_e32 v3, v1, v3, vcc
	v_lshlrev_b32_e32 v28, 2, v3
	v_xor_b32_e32 v3, 32, v1
	v_cmp_lt_i32_e32 vcc, v3, v2
	v_mov_b32_e32 v31, 0x260
	v_readlane_b32 s9, v255, 8
	v_cndmask_b32_e32 v1, v1, v3, vcc
	v_lshlrev_b32_e32 v29, 2, v1
	v_mov_b32_e32 v1, 0
	v_lshl_add_u64 v[12:13], s[14:15], 0, v[0:1]
	v_lshl_add_u64 v[16:17], v[12:13], 0, s[2:3]
	s_mov_b64 s[2:3], 0x1800
	v_lshl_add_u64 v[18:19], v[12:13], 0, s[2:3]
	s_mov_b64 s[2:3], 0x1c00
	v_lshl_add_u64 v[20:21], v[12:13], 0, s[2:3]
	s_lshl_b64 s[2:3], s[6:7], 13
	s_add_u32 s2, s78, s2
	s_addc_u32 s3, s79, s3
	v_lshl_add_u64 v[0:1], s[2:3], 0, v[0:1]
	s_ashr_i32 s75, s74, 31
	v_lshl_add_u64 v[14:15], v[12:13], 0, s[0:1]
	v_lshl_add_u64 v[22:23], v[0:1], 0, s[0:1]
	s_lshl_b64 s[2:3], s[74:75], 13
	v_readlane_b32 s10, v255, 9
	v_readlane_b32 s11, v255, 10
	v_readlane_b32 s12, v255, 11
	v_readlane_b32 s13, v255, 12
	v_readlane_b32 s16, v255, 15
	v_readlane_b32 s17, v255, 16
	v_readlane_b32 s18, v255, 17
	v_readlane_b32 s19, v255, 18
	v_readlane_b32 s20, v255, 19
	v_readlane_b32 s21, v255, 20
	v_readlane_b32 s22, v255, 21
	v_readlane_b32 s23, v255, 22
	global_load_dwordx4 v[132:135], v[12:13], off offset:1024
	global_load_dwordx4 v[136:139], v[12:13], off offset:2048
	global_load_dwordx4 v[140:143], v[12:13], off offset:3072
	global_load_dwordx4 v[144:147], v[14:15], off
	global_load_dwordx4 v[148:151], v[16:17], off
	global_load_dwordx4 v[152:155], v[18:19], off
	global_load_dwordx4 v[156:159], v[20:21], off
